# prologue x row loop: 8 loads per row issued together; out-proj prologue: 3 row-scale loads issued together
# baseline (speedup 1.0000x reference)
; DI void ss_set(ssacc_t* p, float v) { *p = (ssacc_t)__float2ull_rn(v * 4294967296.f); }
; DI float sq8(const f32x4& a, const f32x4& b) { return (a[0] * a[0] + a[1] * a[1]) + (a[2] * a[2] + a[3] * a[3]) + (b[0] * b[0] + b[1] * b[1]) + (b[2] * b[2] + b[3] * b[3]); }
; DI u32x4 pack8(const f32x4& a, const f32x4& b) { u32x4 w; w.x = cvtpk(a[0], a[1]); w.y = cvtpk(a[2], a[3]); w.z = cvtpk(b[0], b[1]); w.w = cvtpk(b[2], b[3]); return w; }
; DI void prologue(PP p, LAS unsigned char* lds) {
;     ...
;         const float* x = p->in[0]; bf16_t* XB = (bf16_t*)(ws + WS_XB); ssacc_t* ss = (ssacc_t*)(ws + WS_SS);
;         for (int m = gw; m < M_; m += NGW) {
;             const f32x4* xr = (const f32x4*)(x + (size_t)m * D_) + lane * 2; float s = 0.f;
; #pragma unroll
;             for (int j = 0; j < 4; ++j) { const f32x4 a = xr[128 * j], b = xr[128 * j + 1]; s += sq8(a, b); *(u32x4*)(XB + (size_t)m * D_ + j * 512 + lane * 8) = pack8(a, b); }
;             s = wave_sum(s); if (lane == 0) ss_set(ss + m, s);
;         }
.LBB0_11:
	v_add_co_u32_e32 v32, vcc, 0xfffff000, v8
	v_lshl_add_u64 v[20:21], v[8:9], 0, s[16:17]
	s_nop 0
	v_addc_co_u32_e32 v33, vcc, -1, v9, vcc
	s_waitcnt lgkmcnt(0)
	global_load_dwordx4 v[16:19], v[32:33], off offset:-2064
	v_lshl_add_u64 v[24:25], s[24:25], 0, v[4:5]
	global_load_dwordx4 v[20:23], v[20:21], off offset:16
	global_load_dwordx4 v[52:55], v[32:33], off offset:-16
	global_load_dwordx4 v[56:59], v[8:9], off offset:-4096
	global_load_dwordx4 v[60:63], v[8:9], off offset:-2064
	global_load_dwordx4 v[64:67], v[8:9], off offset:-2048
	global_load_dwordx4 v[68:71], v[8:9], off offset:-16
	global_load_dwordx4 v[72:75], v[8:9], off
	v_add_co_u32_e32 v48, vcc, s9, v24
	s_waitcnt vmcnt(7)
	v_cvt_pk_bf16_f32 v24, v16, v17
	v_addc_co_u32_e32 v49, vcc, 0, v25, vcc
	v_cvt_pk_bf16_f32 v25, v18, v19
	s_waitcnt vmcnt(6)
	v_cvt_pk_bf16_f32 v26, v20, v21
	v_cvt_pk_bf16_f32 v27, v22, v23
	global_store_dwordx4 v[48:49], v[24:27], off
	v_mul_f32_e32 v6, v17, v17
	v_mul_f32_e32 v17, v19, v19
	v_fmac_f32_e32 v6, v16, v16
	v_fmac_f32_e32 v17, v18, v18
	v_mul_f32_e32 v19, v21, v21
	v_add_f32_e32 v6, v6, v17
	v_fmac_f32_e32 v19, v20, v20
	v_mul_f32_e32 v21, v23, v23
	v_add_f32_e32 v6, v6, v19
	v_fmac_f32_e32 v21, v22, v22
	v_add_f32_e32 v6, v21, v6
	s_waitcnt vmcnt(6)
	v_mov_b32_e32 v24, v52
	v_mov_b32_e32 v25, v53
	v_mov_b32_e32 v26, v54
	v_mov_b32_e32 v27, v55
	v_cvt_pk_bf16_f32 v32, v24, v25
	v_cvt_pk_bf16_f32 v33, v26, v27
	s_waitcnt vmcnt(5)
	v_mov_b32_e32 v28, v56
	v_mov_b32_e32 v29, v57
	v_mov_b32_e32 v30, v58
	v_mov_b32_e32 v31, v59
	v_cvt_pk_bf16_f32 v34, v28, v29
	v_cvt_pk_bf16_f32 v35, v30, v31
	global_store_dwordx4 v[48:49], v[32:35], off offset:1024
	v_mul_f32_e32 v16, v25, v25
	v_mul_f32_e32 v17, v27, v27
	v_mul_f32_e32 v18, v29, v29
	v_fmac_f32_e32 v16, v24, v24
	v_fmac_f32_e32 v17, v26, v26
	v_mul_f32_e32 v19, v31, v31
	v_fmac_f32_e32 v18, v28, v28
	v_add_f32_e32 v16, v16, v17
	v_fmac_f32_e32 v19, v30, v30
	v_add_f32_e32 v16, v16, v18
	v_add_f32_e32 v16, v19, v16
	v_add_f32_e32 v6, v6, v16
	s_waitcnt vmcnt(5)
	v_mov_b32_e32 v32, v60
	v_mov_b32_e32 v33, v61
	v_mov_b32_e32 v34, v62
	v_mov_b32_e32 v35, v63
	v_cvt_pk_bf16_f32 v40, v32, v33
	v_cvt_pk_bf16_f32 v41, v34, v35
	s_waitcnt vmcnt(4)
	v_mov_b32_e32 v36, v64
	v_mov_b32_e32 v37, v65
	v_mov_b32_e32 v38, v66
	v_mov_b32_e32 v39, v67
	v_cvt_pk_bf16_f32 v42, v36, v37
	v_cvt_pk_bf16_f32 v43, v38, v39
	global_store_dwordx4 v[48:49], v[40:43], off offset:2048
	v_mul_f32_e32 v16, v33, v33
	v_mul_f32_e32 v17, v35, v35
	v_mul_f32_e32 v18, v37, v37
	v_fmac_f32_e32 v16, v32, v32
	v_fmac_f32_e32 v17, v34, v34
	v_mul_f32_e32 v19, v39, v39
	v_fmac_f32_e32 v18, v36, v36
	v_add_f32_e32 v16, v16, v17
	v_fmac_f32_e32 v19, v38, v38
	v_add_f32_e32 v16, v16, v18
	v_add_f32_e32 v16, v19, v16
	v_add_f32_e32 v6, v6, v16
	s_waitcnt vmcnt(4)
	v_mov_b32_e32 v40, v68
	v_mov_b32_e32 v41, v69
	v_mov_b32_e32 v42, v70
	v_mov_b32_e32 v43, v71
	v_mul_f32_e32 v16, v41, v41
	v_mul_f32_e32 v17, v43, v43
	s_waitcnt vmcnt(3)
	v_mov_b32_e32 v44, v72
	v_mov_b32_e32 v45, v73
	v_mov_b32_e32 v46, v74
	v_mov_b32_e32 v47, v75
	v_mul_f32_e32 v18, v45, v45
	v_fmac_f32_e32 v16, v40, v40
	v_fmac_f32_e32 v17, v42, v42
	v_mul_f32_e32 v19, v47, v47
	v_fmac_f32_e32 v18, v44, v44
	v_add_f32_e32 v16, v16, v17
	v_add_f32_e32 v16, v16, v18
	v_fmac_f32_e32 v19, v46, v46
	v_add_f32_e32 v16, v19, v16
	v_add_f32_e32 v6, v6, v16
	ds_bpermute_b32 v16, v10, v6
	v_cvt_pk_bf16_f32 v18, v40, v41
	v_cvt_pk_bf16_f32 v19, v42, v43
	v_cvt_pk_bf16_f32 v20, v44, v45
	v_cvt_pk_bf16_f32 v21, v46, v47
	s_waitcnt lgkmcnt(0)
	v_add_f32_e32 v6, v6, v16
	ds_bpermute_b32 v16, v11, v6
	global_store_dwordx4 v[48:49], v[18:21], off offset:3072
	s_waitcnt lgkmcnt(0)
	v_add_f32_e32 v6, v6, v16
	ds_bpermute_b32 v16, v12, v6
	s_waitcnt lgkmcnt(0)
	v_add_f32_e32 v6, v6, v16
	ds_bpermute_b32 v16, v13, v6
	s_waitcnt lgkmcnt(0)
	v_add_f32_e32 v6, v6, v16
	ds_bpermute_b32 v16, v14, v6
	s_waitcnt lgkmcnt(0)
	v_add_f32_e32 v6, v6, v16
	ds_bpermute_b32 v16, v15, v6
	s_and_saveexec_b64 s[18:19], s[6:7]
	s_cbranch_execz .LBB0_10
	s_waitcnt lgkmcnt(0)
	v_add_f32_e32 v6, v6, v16
	v_mul_f32_e32 v6, 0x4f800000, v6
	v_rndne_f32_e32 v6, v6
	v_mul_f32_e32 v16, 0x2f800000, v6
	v_floor_f32_e32 v17, v16
	v_fmac_f32_e32 v6, 0xcf800000, v17
	v_cvt_u32_f32_e32 v16, v6
	v_cvt_u32_f32_e32 v17, v17
	s_add_u32 s20, s24, s3
	s_addc_u32 s21, s25, s5
	global_store_dwordx2 v7, v[16:17], s[20:21]
	s_branch .LBB0_10

; DI float ss_get(const ssacc_t* p) { const ssacc_t v = *p; return (float)(unsigned)(v >> 32) + (float)(unsigned)(v & 0xffffffffull) * 2.3283064365386963e-10f; }
;     DI ssacc_t* ss_mla() const { return (ssacc_t*)(ws + WS_SS) + (size_t)(SS_MLA + l) * M_; }
; __global__ void __launch_bounds__(512, 2) hymba_fwd(Params p_unused) {
;     ...
;           { pg8::StaticOrder S; S.init(M_, 2048, (int)gridDim.x, (int)blockIdx.x);
;             const int ui = threadIdx.x >> 8, rr = threadIdx.x & 255; Unit u;
;             if (S.next(ui, u)) { const int row = u.pm * 256 + rr; const float rm = rsqrtf(ss_get(ss_mla + row) * (1.f / 1024.f) + EPS_), rsm = rsqrtf(ss_get(ss_ssm + row) * (1.f / 512.f) + EPS_), rd = rsqrtf(ss_get(ss_dil + row) * (1.f / 512.f) + EPS_);
;                 FT[(ui * 2 + 0) * 256 + rr] = rsm / rm; FT[(ui * 2 + 1) * 256 + rr] = rm / rd; }
.LBB0_1250:
	s_or_b64 exec, exec, s[6:7]
	v_readlane_b32 s10, v253, 3
	v_readlane_b32 s11, v253, 4
	s_waitcnt lgkmcnt(0)
	s_barrier
	s_load_dwordx2 s[6:7], s[10:11], 0xd8
	s_mov_b64 s[8:9], exec
	v_readlane_b32 s0, v254, 30
	v_readlane_b32 s1, v254, 31
	s_and_b64 s[0:1], s[8:9], s[0:1]
	s_mov_b64 exec, s[0:1]
	s_or_b64 exec, exec, s[8:9]
	s_mov_b64 s[8:9], exec
	v_readlane_b32 s0, v254, 30
	v_readlane_b32 s1, v254, 31
	s_and_b64 s[0:1], s[8:9], s[0:1]
	s_mov_b64 exec, s[0:1]
	s_cbranch_execz .LBB0_1252
	v_readlane_b32 s0, v255, 3
	v_readlane_b32 s1, v255, 4
	s_lshl_b64 s[0:1], s[0:1], 3
	v_and_b32_e32 v0, 0xff, v188
	s_waitcnt lgkmcnt(0)
	s_add_u32 s0, s6, s0
	v_lshl_or_b32 v0, v194, 8, v0
	s_addc_u32 s1, s7, s1
	v_ashrrev_i32_e32 v1, 31, v0
	v_lshl_add_u64 v[0:1], v[0:1], 3, s[0:1]
	v_add_co_u32_e32 v2, vcc, 0x29610000, v0
	s_min_u32 s0, s88, 32
	s_nop 0
	v_addc_co_u32_e32 v3, vcc, 0, v1, vcc
	global_load_dwordx2 v[2:3], v[2:3], off
	v_add_co_u32_e32 v212, vcc, 0x295d0000, v0
	s_nop 1
	v_addc_co_u32_e32 v213, vcc, 0, v1, vcc
	v_add_co_u32_e32 v214, vcc, 0x29650000, v0
	s_nop 1
	v_addc_co_u32_e32 v215, vcc, 0, v1, vcc
	global_load_dwordx2 v[216:217], v[212:213], off
	global_load_dwordx2 v[218:219], v[214:215], off
	s_sub_i32 s1, 32, s0
	s_mov_b32 s4, 0x295d0000
	s_waitcnt vmcnt(2)
	v_mov_b32_e32 v128, v3
	v_lshlrev_b64 v[4:5], s0, v[128:129]
	v_min_u32_e32 v3, 1, v4
	v_or_b32_e32 v3, v5, v3
	v_cvt_f32_u32_e32 v3, v3
	v_cvt_f32_u32_e32 v2, v2
	v_ldexp_f32 v3, v3, s1
	v_fmac_f32_e32 v3, 0x2f800000, v2
	v_fmamk_f32 v2, v3, 0x3a800000, v195
	v_cmp_gt_f32_e32 vcc, s27, v2
	v_mul_f32_e32 v3, 0x4b800000, v2
	s_nop 0
	v_cndmask_b32_e32 v2, v2, v3, vcc
	v_rsq_f32_e32 v2, v2
	s_nop 0
	v_mul_f32_e32 v3, 0x45800000, v2
	v_cndmask_b32_e32 v6, v2, v3, vcc
	v_add_co_u32_e32 v2, vcc, s4, v0
	s_mov_b32 s4, 0x29650000
	s_nop 0
	v_addc_co_u32_e32 v3, vcc, 0, v1, vcc
	s_waitcnt vmcnt(1)
	v_mov_b32_e32 v2, v216
	v_mov_b32_e32 v3, v217
	v_mov_b32_e32 v128, v3
	v_lshlrev_b64 v[4:5], s0, v[128:129]
	v_min_u32_e32 v3, 1, v4
	v_or_b32_e32 v3, v5, v3
	v_cvt_f32_u32_e32 v3, v3
	v_cvt_f32_u32_e32 v2, v2
	v_ldexp_f32 v3, v3, s1
	v_fmac_f32_e32 v3, 0x2f800000, v2
	v_fmamk_f32 v2, v3, 0x3b000000, v195
	v_cmp_gt_f32_e32 vcc, s27, v2
	v_mul_f32_e32 v3, 0x4b800000, v2
	s_nop 0
	v_cndmask_b32_e32 v2, v2, v3, vcc
	v_rsq_f32_e32 v2, v2
	s_nop 0
	v_mul_f32_e32 v3, 0x45800000, v2
	v_cndmask_b32_e32 v4, v2, v3, vcc
	v_add_co_u32_e32 v0, vcc, s4, v0
	s_nop 1
	v_addc_co_u32_e32 v1, vcc, 0, v1, vcc
	s_waitcnt vmcnt(0)
	v_mov_b32_e32 v0, v218
	v_mov_b32_e32 v1, v219
	v_mov_b32_e32 v128, v1
	v_lshlrev_b64 v[2:3], s0, v[128:129]
	v_min_u32_e32 v1, 1, v2
	v_or_b32_e32 v1, v3, v1
	v_cvt_f32_u32_e32 v1, v1
	v_cvt_f32_u32_e32 v0, v0
	v_ldexp_f32 v1, v1, s1
	v_fmac_f32_e32 v1, 0x2f800000, v0
	v_fmamk_f32 v0, v1, 0x3b000000, v195
	v_cmp_gt_f32_e32 vcc, s27, v0
	v_mul_f32_e32 v1, 0x4b800000, v0
	s_nop 0
	v_cndmask_b32_e32 v0, v0, v1, vcc
	v_rsq_f32_e32 v0, v0
	s_nop 0
	v_mul_f32_e32 v1, 0x45800000, v0
	v_cndmask_b32_e32 v0, v0, v1, vcc
	v_div_scale_f32 v1, s[0:1], v6, v6, v4
	v_rcp_f32_e32 v2, v1
	s_nop 0
	v_fma_f32 v3, -v1, v2, 1.0
	v_fmac_f32_e32 v2, v3, v2
	v_div_scale_f32 v3, vcc, v4, v6, v4
	v_mul_f32_e32 v5, v3, v2
	v_fma_f32 v7, -v1, v5, v3
	v_fmac_f32_e32 v5, v7, v2
	v_fma_f32 v1, -v1, v5, v3
	v_div_fmas_f32 v1, v1, v2, v5
	v_div_scale_f32 v2, s[0:1], v0, v0, v6
	v_rcp_f32_e32 v3, v2
	v_div_fixup_f32 v1, v1, v6, v4
	v_fma_f32 v4, -v2, v3, 1.0
	v_fmac_f32_e32 v3, v4, v3
	v_div_scale_f32 v4, vcc, v6, v0, v6
	v_mul_f32_e32 v5, v4, v3
	v_fma_f32 v7, -v2, v5, v4
	v_fmac_f32_e32 v5, v7, v3
	v_fma_f32 v2, -v2, v5, v4
	v_div_fmas_f32 v2, v2, v3, v5
	v_div_fixup_f32 v0, v2, v0, v6
	ds_write2st64_b32 v197, v1, v0 offset1:4
